# latent attention finalize de-serialised as well (the 512-per-layer instance)
# baseline (speedup 1.0000x reference)
.LBB0_910:
	v_add_f32_e32 v1, 0, v101
	v_add_f32_e32 v1, v102, v1
	v_add_f32_e32 v1, v103, v1
	v_add_f32_e32 v1, v104, v1
	v_add_f32_e32 v1, v105, v1
	v_add_f32_e32 v1, v106, v1
	v_add_f32_e32 v1, v107, v1
	v_add_f32_e32 v1, v108, v1
	v_add_f32_e32 v1, v109, v1
	v_add_f32_e32 v1, v110, v1
	v_add_f32_e32 v1, v111, v1
	v_add_f32_e32 v1, v112, v1
	v_add_f32_e32 v1, v113, v1
	v_exp_f32_e32 v14, v80
	v_add_f32_e32 v1, v114, v1
	v_exp_f32_e32 v80, v81
	v_add_f32_e32 v1, v115, v1
	v_exp_f32_e32 v81, v82
	v_add_f32_e32 v1, v116, v1
	v_exp_f32_e32 v82, v83
	v_add_f32_e32 v1, v15, v1
	v_add_f32_e32 v15, 0, v14
	v_exp_f32_e32 v83, v84
	v_exp_f32_e32 v84, v85
	v_exp_f32_e32 v85, v86
	v_exp_f32_e32 v86, v87
	v_add_f32_e32 v15, v80, v15
	v_add_f32_e32 v15, v81, v15
	v_add_f32_e32 v15, v82, v15
	v_readlane_b32 s4, v255, 43
	v_add_f32_e32 v15, v83, v15
	v_cvt_pkrtz_f16_f32 v80, v14, v80
	v_cvt_pkrtz_f16_f32 v81, v81, v82
	v_cvt_pkrtz_f16_f32 v82, v83, v84
	v_cvt_pkrtz_f16_f32 v83, v85, v86
	v_readlane_b32 s5, v255, 44
	s_waitcnt vmcnt(0)
	s_nop 0
	v_mfma_f32_32x32x16_f16 v[64:79], v[2:5], v[80:83], v[64:79]
	v_mov_b64_e32 v[2:3], s[4:5]
	s_barrier
	flat_load_dword v4, v[2:3] sc0 sc1
	v_readlane_b32 s4, v255, 45
	v_readlane_b32 s5, v255, 46
	v_exp_f32_e32 v87, v88
	v_add_f32_e32 v15, v84, v15
	v_mov_b64_e32 v[102:103], s[4:5]
	v_exp_f32_e32 v88, v89
	v_mfma_f32_32x32x16_f16 v[48:63], v[6:9], v[80:83], v[48:63]
	flat_load_dword v6, v[102:103] sc0 sc1
	global_load_dwordx4 v[104:107], v210, s[34:35]
	global_load_dwordx4 v[108:111], v210, s[34:35] offset:32
	global_load_dwordx4 v[112:115], v210, s[34:35] offset:64
	global_load_dwordx4 v[116:119], v210, s[34:35] offset:96
	global_load_dwordx4 v[120:123], v210, s[34:35] offset:128
	global_load_dwordx4 v[124:127], v210, s[34:35] offset:160
	global_load_dwordx4 v[128:131], v210, s[34:35] offset:192
	global_load_dwordx4 v[132:135], v210, s[34:35] offset:224
	s_waitcnt vmcnt(0)
	ds_bpermute_b32 v2, v153, v1
	v_add_f32_e32 v15, v85, v15
	v_exp_f32_e32 v89, v90
	v_add_f32_e32 v15, v86, v15
	v_exp_f32_e32 v90, v91
	v_add_f32_e32 v15, v87, v15
	v_exp_f32_e32 v91, v92
	v_add_f32_e32 v15, v88, v15
	v_exp_f32_e32 v92, v93
	v_add_f32_e32 v15, v89, v15
	v_exp_f32_e32 v93, v94
	s_waitcnt lgkmcnt(0)
	v_add_f32_e32 v1, v1, v2
	v_add_f32_e32 v15, v90, v15
	v_exp_f32_e32 v94, v95
	v_div_scale_f32 v3, s[4:5], v1, v1, 1.0
	v_add_f32_e32 v15, v91, v15
	v_rcp_f32_e32 v5, v3
	v_add_f32_e32 v15, v92, v15
	v_add_f32_e32 v15, v93, v15
	v_add_f32_e32 v15, v94, v15
	v_add_f32_e32 v15, v100, v15
	v_fma_f32 v7, -v3, v5, 1.0
	ds_bpermute_b32 v2, v153, v15
	v_fmac_f32_e32 v5, v7, v5
	v_div_scale_f32 v7, vcc, 1.0, v1, 1.0
	v_mul_f32_e32 v8, v7, v5
	v_fma_f32 v9, -v3, v8, v7
	v_fmac_f32_e32 v8, v9, v5
	v_fma_f32 v3, -v3, v8, v7
	v_cvt_pkrtz_f16_f32 v84, v87, v88
	v_cvt_pkrtz_f16_f32 v85, v89, v90
	v_cvt_pkrtz_f16_f32 v86, v91, v92
	v_cvt_pkrtz_f16_f32 v87, v93, v94
	s_waitcnt lgkmcnt(0)
	v_add_f32_e32 v2, v15, v2
	v_div_fmas_f32 v3, v3, v5, v8
	v_mfma_f32_32x32x16_f16 v[64:79], v[10:13], v[84:87], v[64:79]
	v_div_fixup_f32 v12, v3, v1, 1.0
	s_mov_b32 s3, s59
	v_div_scale_f32 v1, s[4:5], v2, v2, v4
	v_rcp_f32_e32 v3, v1
	v_mfma_f32_32x32x16_f16 v[48:63], v[96:99], v[84:87], v[48:63]
	v_fma_f32 v5, -v1, v3, 1.0
	v_fmac_f32_e32 v3, v5, v3
	v_div_scale_f32 v5, vcc, v4, v2, v4
	v_mul_f32_e32 v7, v5, v3
	v_fma_f32 v8, -v1, v7, v5
	v_fmac_f32_e32 v7, v8, v3
	v_fma_f32 v1, -v1, v7, v5
	v_div_fmas_f32 v1, v1, v3, v7
	v_div_fixup_f32 v14, v1, v2, v4
	s_nop 1
	v_pk_mul_f32 v[48:49], v[48:49], v[14:15] op_sel_hi:[1,0]
	v_pk_mul_f32 v[2:3], v[76:77], v[14:15] op_sel_hi:[1,0]
	v_pk_fma_f32 v[16:17], v[16:17], v[12:13], v[48:49] op_sel_hi:[1,0,1] neg_lo:[0,0,1] neg_hi:[0,0,1]
	v_pk_mul_f32 v[50:51], v[50:51], v[14:15] op_sel_hi:[1,0]
	v_pk_fma_f32 v[4:5], v[44:45], v[12:13], v[2:3] op_sel_hi:[1,0,1] neg_lo:[0,0,1] neg_hi:[0,0,1]
	v_pk_mul_f32 v[2:3], v[78:79], v[14:15] op_sel_hi:[1,0]
	v_pk_mul_f32 v[48:49], v[16:17], v[16:17]
	v_pk_fma_f32 v[18:19], v[18:19], v[12:13], v[50:51] op_sel_hi:[1,0,1] neg_lo:[0,0,1] neg_hi:[0,0,1]
	v_pk_mul_f32 v[52:53], v[52:53], v[14:15] op_sel_hi:[1,0]
	v_pk_mul_f32 v[54:55], v[54:55], v[14:15] op_sel_hi:[1,0]
	v_pk_mul_f32 v[56:57], v[56:57], v[14:15] op_sel_hi:[1,0]
	v_pk_mul_f32 v[58:59], v[58:59], v[14:15] op_sel_hi:[1,0]
	v_pk_mul_f32 v[60:61], v[60:61], v[14:15] op_sel_hi:[1,0]
	v_pk_mul_f32 v[62:63], v[62:63], v[14:15] op_sel_hi:[1,0]
	v_pk_mul_f32 v[64:65], v[64:65], v[14:15] op_sel_hi:[1,0]
	v_pk_mul_f32 v[66:67], v[66:67], v[14:15] op_sel_hi:[1,0]
	v_pk_mul_f32 v[68:69], v[68:69], v[14:15] op_sel_hi:[1,0]
	v_pk_mul_f32 v[70:71], v[70:71], v[14:15] op_sel_hi:[1,0]
	v_pk_mul_f32 v[72:73], v[72:73], v[14:15] op_sel_hi:[1,0]
	v_pk_mul_f32 v[14:15], v[74:75], v[14:15] op_sel_hi:[1,0]
	v_pk_fma_f32 v[2:3], v[46:47], v[12:13], v[2:3] op_sel_hi:[1,0,1] neg_lo:[0,0,1] neg_hi:[0,0,1]
	v_pk_mul_f32 v[50:51], v[18:19], v[18:19]
	v_pk_fma_f32 v[20:21], v[20:21], v[12:13], v[52:53] op_sel_hi:[1,0,1] neg_lo:[0,0,1] neg_hi:[0,0,1]
	v_pk_fma_f32 v[22:23], v[22:23], v[12:13], v[54:55] op_sel_hi:[1,0,1] neg_lo:[0,0,1] neg_hi:[0,0,1]
	v_pk_fma_f32 v[24:25], v[24:25], v[12:13], v[56:57] op_sel_hi:[1,0,1] neg_lo:[0,0,1] neg_hi:[0,0,1]
	v_pk_fma_f32 v[26:27], v[26:27], v[12:13], v[58:59] op_sel_hi:[1,0,1] neg_lo:[0,0,1] neg_hi:[0,0,1]
	v_pk_fma_f32 v[28:29], v[28:29], v[12:13], v[60:61] op_sel_hi:[1,0,1] neg_lo:[0,0,1] neg_hi:[0,0,1]
	v_pk_fma_f32 v[30:31], v[30:31], v[12:13], v[62:63] op_sel_hi:[1,0,1] neg_lo:[0,0,1] neg_hi:[0,0,1]
	v_pk_fma_f32 v[32:33], v[32:33], v[12:13], v[64:65] op_sel_hi:[1,0,1] neg_lo:[0,0,1] neg_hi:[0,0,1]
	v_pk_fma_f32 v[34:35], v[34:35], v[12:13], v[66:67] op_sel_hi:[1,0,1] neg_lo:[0,0,1] neg_hi:[0,0,1]
	v_pk_fma_f32 v[36:37], v[36:37], v[12:13], v[68:69] op_sel_hi:[1,0,1] neg_lo:[0,0,1] neg_hi:[0,0,1]
	v_pk_fma_f32 v[38:39], v[38:39], v[12:13], v[70:71] op_sel_hi:[1,0,1] neg_lo:[0,0,1] neg_hi:[0,0,1]
	v_pk_fma_f32 v[40:41], v[40:41], v[12:13], v[72:73] op_sel_hi:[1,0,1] neg_lo:[0,0,1] neg_hi:[0,0,1]
	v_pk_fma_f32 v[12:13], v[42:43], v[12:13], v[14:15] op_sel_hi:[1,0,1] neg_lo:[0,0,1] neg_hi:[0,0,1]
	v_add_f32_e32 v42, v48, v49
	v_add_f32_e32 v42, v50, v42
	v_pk_mul_f32 v[52:53], v[20:21], v[20:21]
	v_add_f32_e32 v42, v51, v42
	v_add_f32_e32 v42, v52, v42
	v_pk_mul_f32 v[54:55], v[22:23], v[22:23]
	v_add_f32_e32 v42, v53, v42
	v_add_f32_e32 v42, v54, v42
	v_pk_mul_f32 v[56:57], v[24:25], v[24:25]
	v_add_f32_e32 v42, v55, v42
	v_add_f32_e32 v42, v56, v42
	v_pk_mul_f32 v[58:59], v[26:27], v[26:27]
	v_add_f32_e32 v42, v57, v42
	v_add_f32_e32 v42, v58, v42
	v_pk_mul_f32 v[60:61], v[28:29], v[28:29]
	v_add_f32_e32 v42, v59, v42
	v_add_f32_e32 v42, v60, v42
	v_pk_mul_f32 v[62:63], v[30:31], v[30:31]
	v_add_f32_e32 v42, v61, v42
	v_add_f32_e32 v42, v62, v42
	v_pk_mul_f32 v[64:65], v[32:33], v[32:33]
	v_add_f32_e32 v42, v63, v42
	v_add_f32_e32 v42, v64, v42
	v_pk_mul_f32 v[66:67], v[34:35], v[34:35]
	v_add_f32_e32 v42, v65, v42
	v_add_f32_e32 v42, v66, v42
	v_pk_mul_f32 v[68:69], v[36:37], v[36:37]
	v_add_f32_e32 v42, v67, v42
	v_add_f32_e32 v42, v68, v42
	v_pk_mul_f32 v[70:71], v[38:39], v[38:39]
	v_add_f32_e32 v42, v69, v42
	v_add_f32_e32 v42, v70, v42
	v_pk_mul_f32 v[72:73], v[40:41], v[40:41]
	v_add_f32_e32 v42, v71, v42
	v_add_f32_e32 v42, v72, v42
	v_pk_mul_f32 v[14:15], v[12:13], v[12:13]
	v_add_f32_e32 v42, v73, v42
	v_add_f32_e32 v14, v14, v42
	v_pk_mul_f32 v[44:45], v[4:5], v[4:5]
	v_add_f32_e32 v14, v15, v14
	v_add_f32_e32 v14, v44, v14
	v_pk_mul_f32 v[46:47], v[2:3], v[2:3]
	v_add_f32_e32 v14, v45, v14
	v_add_f32_e32 v14, v46, v14
	v_add_f32_e32 v14, v47, v14
	ds_bpermute_b32 v15, v153, v14
	v_sub_f32_e32 v1, 1.0, v6
	v_lshlrev_b64 v[6:7], 11, v[148:149]
	v_lshl_add_u64 v[6:7], s[64:65], 0, v[6:7]
	v_lshl_add_u64 v[6:7], v[6:7], 0, s[2:3]
	s_waitcnt lgkmcnt(0)
	v_add_f32_e32 v14, v14, v15
	v_fmamk_f32 v14, v14, 0x3c800000, v213
	v_cmp_gt_f32_e32 vcc, s38, v14
	v_mul_f32_e32 v15, 0x4b800000, v14
	v_lshlrev_b32_e32 v76, 3, v152
	v_cndmask_b32_e32 v14, v14, v15, vcc
	v_rsq_f32_e32 v14, v14
	v_mov_b32_e32 v77, v211
	v_lshl_add_u64 v[6:7], v[6:7], 0, v[76:77]
	v_mul_f32_e32 v15, 0x45800000, v14
	v_cndmask_b32_e32 v14, v14, v15, vcc
	v_mul_f32_e32 v14, v1, v14
	v_pk_mul_f32 v[16:17], v[16:17], v[14:15] op_sel_hi:[1,0]
	v_pk_mul_f32 v[12:13], v[12:13], v[14:15] op_sel_hi:[1,0]
	v_pk_mul_f32 v[8:9], v[104:105], v[16:17]
	v_pk_mul_f32 v[16:17], v[18:19], v[14:15] op_sel_hi:[1,0]
	v_cvt_pk_f16_f32 v8, v8, v9
	v_pk_mul_f32 v[10:11], v[106:107], v[16:17]
	v_pk_mul_f32 v[16:17], v[20:21], v[14:15] op_sel_hi:[1,0]
	v_cvt_pk_f16_f32 v9, v10, v11
	global_store_dwordx2 v[6:7], v[8:9], off offset:1536
	v_pk_mul_f32 v[4:5], v[4:5], v[14:15] op_sel_hi:[1,0]
	v_pk_mul_f32 v[2:3], v[2:3], v[14:15] op_sel_hi:[1,0]
	v_pk_mul_f32 v[8:9], v[108:109], v[16:17]
	v_pk_mul_f32 v[16:17], v[22:23], v[14:15] op_sel_hi:[1,0]
	v_cvt_pk_f16_f32 v8, v8, v9
	v_pk_mul_f32 v[10:11], v[110:111], v[16:17]
	v_pk_mul_f32 v[16:17], v[24:25], v[14:15] op_sel_hi:[1,0]
	v_cvt_pk_f16_f32 v9, v10, v11
	global_store_dwordx2 v[6:7], v[8:9], off offset:1552
	v_pk_mul_f32 v[8:9], v[112:113], v[16:17]
	v_pk_mul_f32 v[16:17], v[26:27], v[14:15] op_sel_hi:[1,0]
	v_cvt_pk_f16_f32 v8, v8, v9
	v_pk_mul_f32 v[10:11], v[114:115], v[16:17]
	v_pk_mul_f32 v[16:17], v[28:29], v[14:15] op_sel_hi:[1,0]
	v_cvt_pk_f16_f32 v9, v10, v11
	global_store_dwordx2 v[6:7], v[8:9], off offset:1568
	v_pk_mul_f32 v[8:9], v[116:117], v[16:17]
	v_pk_mul_f32 v[16:17], v[30:31], v[14:15] op_sel_hi:[1,0]
	v_cvt_pk_f16_f32 v8, v8, v9
	v_pk_mul_f32 v[10:11], v[118:119], v[16:17]
	v_pk_mul_f32 v[16:17], v[32:33], v[14:15] op_sel_hi:[1,0]
	v_cvt_pk_f16_f32 v9, v10, v11
	global_store_dwordx2 v[6:7], v[8:9], off offset:1584
	v_pk_mul_f32 v[8:9], v[120:121], v[16:17]
	v_pk_mul_f32 v[16:17], v[34:35], v[14:15] op_sel_hi:[1,0]
	v_cvt_pk_f16_f32 v8, v8, v9
	v_pk_mul_f32 v[10:11], v[122:123], v[16:17]
	v_pk_mul_f32 v[16:17], v[36:37], v[14:15] op_sel_hi:[1,0]
	v_cvt_pk_f16_f32 v9, v10, v11
	global_store_dwordx2 v[6:7], v[8:9], off offset:1600
	v_pk_mul_f32 v[8:9], v[124:125], v[16:17]
	v_pk_mul_f32 v[16:17], v[38:39], v[14:15] op_sel_hi:[1,0]
	v_cvt_pk_f16_f32 v8, v8, v9
	v_pk_mul_f32 v[10:11], v[126:127], v[16:17]
	v_pk_mul_f32 v[16:17], v[40:41], v[14:15] op_sel_hi:[1,0]
	v_cvt_pk_f16_f32 v9, v10, v11
	global_store_dwordx2 v[6:7], v[8:9], off offset:1616
	v_pk_mul_f32 v[8:9], v[128:129], v[16:17]
	v_pk_mul_f32 v[10:11], v[130:131], v[12:13]
	v_cvt_pk_f16_f32 v8, v8, v9
	v_cvt_pk_f16_f32 v9, v10, v11
	global_store_dwordx2 v[6:7], v[8:9], off offset:1632
	v_pk_mul_f32 v[4:5], v[132:133], v[4:5]
	v_pk_mul_f32 v[2:3], v[134:135], v[2:3]
	v_cvt_pk_f16_f32 v4, v4, v5
	v_cvt_pk_f16_f32 v5, v2, v3
	global_store_dwordx2 v[6:7], v[4:5], off offset:1648
